# P0 weight transposes: the f32 weight elements are fetched with the nt cache policy
# speedup vs baseline: 1.0248x; 1.0099x over previous
.LBB0_9:
	s_or_b64 exec, exec, s[74:75]
	s_load_dwordx16 s[16:31], s[62:63], 0x40
	v_lshlrev_b32_e32 v40, 6, v2
	v_or_b32_e32 v39, v40, v16
	v_max_i32_e32 v2, 0, v38
	v_cmp_lt_i32_e32 vcc, -1, v38
	s_waitcnt lgkmcnt(0)
	v_lshl_add_u64 v[42:43], v[2:3], 2, s[18:19]
	v_or_b32_e32 v2, 2, v39
	v_mad_i64_i32 v[46:47], s[36:37], v2, s60, v[42:43]
	v_or_b32_e32 v2, 4, v39
	v_mad_i64_i32 v[48:49], s[36:37], v2, s60, v[42:43]
	v_or_b32_e32 v2, 6, v39
	v_mad_i64_i32 v[54:55], s[36:37], v2, s60, v[42:43]
	v_or_b32_e32 v2, 8, v39
	v_mad_i64_i32 v[56:57], s[36:37], v2, s60, v[42:43]
	v_or_b32_e32 v2, 10, v39
	v_mad_i64_i32 v[58:59], s[36:37], v2, s60, v[42:43]
	v_or_b32_e32 v2, 12, v39
	v_mad_i64_i32 v[44:45], s[36:37], v39, s60, v[42:43]
	v_mad_i64_i32 v[60:61], s[36:37], v2, s60, v[42:43]
	v_or_b32_e32 v2, 14, v39
	v_mad_i64_i32 v[62:63], s[36:37], v2, s60, v[42:43]
	global_load_dword v2, v[44:45], off nt
	global_load_dword v41, v[46:47], off nt
	global_load_dword v53, v[48:49], off nt
	global_load_dword v64, v[54:55], off nt
	global_load_dword v66, v[56:57], off nt
	global_load_dword v67, v[58:59], off nt
	global_load_dword v68, v[60:61], off nt
	global_load_dword v69, v[62:63], off nt
	v_or_b32_e32 v44, 16, v39
	v_mad_i64_i32 v[44:45], s[36:37], v44, s60, v[42:43]
	v_or_b32_e32 v46, 18, v39
	v_or_b32_e32 v48, 20, v39
	v_or_b32_e32 v54, 22, v39
	v_or_b32_e32 v56, 24, v39
	v_or_b32_e32 v58, 26, v39
	v_or_b32_e32 v60, 28, v39
	v_or_b32_e32 v62, 30, v39
	v_mad_i64_i32 v[46:47], s[36:37], v46, s60, v[42:43]
	v_mad_i64_i32 v[48:49], s[36:37], v48, s60, v[42:43]
	v_mad_i64_i32 v[54:55], s[36:37], v54, s60, v[42:43]
	v_mad_i64_i32 v[56:57], s[36:37], v56, s60, v[42:43]
	v_mad_i64_i32 v[58:59], s[36:37], v58, s60, v[42:43]
	v_mad_i64_i32 v[60:61], s[36:37], v60, s60, v[42:43]
	v_mad_i64_i32 v[62:63], s[36:37], v62, s60, v[42:43]
	global_load_dword v70, v[44:45], off nt
	global_load_dword v71, v[46:47], off nt
	global_load_dword v72, v[48:49], off nt
	global_load_dword v73, v[54:55], off nt
	global_load_dword v74, v[56:57], off nt
	global_load_dword v75, v[58:59], off nt
	global_load_dword v76, v[60:61], off nt
	global_load_dword v77, v[62:63], off nt
	v_or_b32_e32 v44, 32, v39
	v_or_b32_e32 v46, 34, v39
	v_or_b32_e32 v48, 36, v39
	v_or_b32_e32 v54, 38, v39
	v_or_b32_e32 v60, 44, v39
	v_mad_i64_i32 v[44:45], s[36:37], v44, s60, v[42:43]
	v_mad_i64_i32 v[46:47], s[36:37], v46, s60, v[42:43]
	v_mad_i64_i32 v[48:49], s[36:37], v48, s60, v[42:43]
	v_mad_i64_i32 v[54:55], s[36:37], v54, s60, v[42:43]
	v_or_b32_e32 v56, 40, v39
	v_or_b32_e32 v58, 42, v39
	v_mad_i64_i32 v[60:61], s[36:37], v60, s60, v[42:43]
	v_or_b32_e32 v62, 46, v39
	v_mad_i64_i32 v[56:57], s[36:37], v56, s60, v[42:43]
	v_mad_i64_i32 v[58:59], s[36:37], v58, s60, v[42:43]
	v_mad_i64_i32 v[62:63], s[36:37], v62, s60, v[42:43]
	global_load_dword v78, v[44:45], off nt
	global_load_dword v79, v[46:47], off nt
	global_load_dword v80, v[48:49], off nt
	global_load_dword v81, v[54:55], off nt
	global_load_dword v82, v[56:57], off nt
	global_load_dword v83, v[58:59], off nt
	s_nop 0
	global_load_dword v60, v[60:61], off nt
	s_nop 0
	global_load_dword v61, v[62:63], off nt
	v_or_b32_e32 v44, 48, v39
	v_or_b32_e32 v46, 50, v39
	v_or_b32_e32 v48, 52, v39
	v_or_b32_e32 v54, 54, v39
	v_mad_i64_i32 v[44:45], s[36:37], v44, s60, v[42:43]
	v_mad_i64_i32 v[46:47], s[36:37], v46, s60, v[42:43]
	v_mad_i64_i32 v[48:49], s[36:37], v48, s60, v[42:43]
	v_mad_i64_i32 v[54:55], s[36:37], v54, s60, v[42:43]
	v_or_b32_e32 v56, 56, v39
	v_or_b32_e32 v58, 58, v39
	v_mad_i64_i32 v[56:57], s[36:37], v56, s60, v[42:43]
	v_mad_i64_i32 v[58:59], s[36:37], v58, s60, v[42:43]
	global_load_dword v62, v[44:45], off nt
	s_nop 0
	global_load_dword v46, v[46:47], off nt
	s_nop 0
	global_load_dword v47, v[48:49], off nt
	s_nop 0
	global_load_dword v48, v[54:55], off nt
	global_load_dword v49, v[56:57], off nt
	s_nop 0
	global_load_dword v54, v[58:59], off nt
	v_or_b32_e32 v44, 60, v39
	v_or_b32_e32 v39, 62, v39
	v_mad_i64_i32 v[44:45], s[36:37], v44, s60, v[42:43]
	v_mad_i64_i32 v[42:43], s[36:37], v39, s60, v[42:43]
	global_load_dword v39, v[44:45], off nt
	s_nop 0
	global_load_dword v42, v[42:43], off nt
	s_waitcnt vmcnt(31)
	v_cndmask_b32_e32 v2, 0, v2, vcc
	s_waitcnt vmcnt(30)
	v_cndmask_b32_e32 v38, 0, v41, vcc
	ds_write2_b32 v17, v2, v38 offset1:66
	s_waitcnt vmcnt(29)
	v_cndmask_b32_e32 v2, 0, v53, vcc
	s_waitcnt vmcnt(28)
	v_cndmask_b32_e32 v38, 0, v64, vcc
	ds_write2_b32 v17, v2, v38 offset0:132 offset1:198
	s_waitcnt vmcnt(27)
	v_cndmask_b32_e32 v2, 0, v66, vcc
	s_waitcnt vmcnt(26)
	v_cndmask_b32_e32 v38, 0, v67, vcc
	ds_write2_b32 v27, v2, v38 offset0:8 offset1:74
	s_waitcnt vmcnt(25)
	v_cndmask_b32_e32 v2, 0, v68, vcc
	s_waitcnt vmcnt(24)
	v_cndmask_b32_e32 v38, 0, v69, vcc
	ds_write2_b32 v27, v2, v38 offset0:140 offset1:206
	v_add3_u32 v66, v18, v24, v37
	v_ashrrev_i32_e32 v41, 31, v40
	v_ashrrev_i32_e32 v67, 31, v66
	v_lshlrev_b64 v[68:69], 11, v[66:67]
	s_waitcnt vmcnt(23)
	v_cndmask_b32_e32 v2, 0, v70, vcc
	s_waitcnt vmcnt(22)
	v_cndmask_b32_e32 v38, 0, v71, vcc
	ds_write2_b32 v28, v2, v38 offset0:16 offset1:82
	s_waitcnt vmcnt(21)
	v_cndmask_b32_e32 v2, 0, v72, vcc
	s_waitcnt vmcnt(20)
	v_cndmask_b32_e32 v38, 0, v73, vcc
	ds_write2_b32 v28, v2, v38 offset0:148 offset1:214
	s_waitcnt vmcnt(19)
	v_cndmask_b32_e32 v2, 0, v74, vcc
	s_waitcnt vmcnt(18)
	v_cndmask_b32_e32 v38, 0, v75, vcc
	ds_write2_b32 v29, v2, v38 offset0:24 offset1:90
	s_waitcnt vmcnt(17)
	v_cndmask_b32_e32 v2, 0, v76, vcc
	s_waitcnt vmcnt(16)
	v_cndmask_b32_e32 v38, 0, v77, vcc
	ds_write2_b32 v29, v2, v38 offset0:156 offset1:222
	s_waitcnt vmcnt(15)
	v_cndmask_b32_e32 v2, 0, v78, vcc
	s_waitcnt vmcnt(14)
	v_cndmask_b32_e32 v38, 0, v79, vcc
	ds_write2_b32 v30, v2, v38 offset0:32 offset1:98
	s_waitcnt vmcnt(13)
	v_cndmask_b32_e32 v2, 0, v80, vcc
	s_waitcnt vmcnt(12)
	v_cndmask_b32_e32 v38, 0, v81, vcc
	ds_write2_b32 v30, v2, v38 offset0:164 offset1:230
	s_waitcnt vmcnt(11)
	v_cndmask_b32_e32 v2, 0, v82, vcc
	s_waitcnt vmcnt(10)
	v_cndmask_b32_e32 v38, 0, v83, vcc
	ds_write2_b32 v31, v2, v38 offset0:40 offset1:106
	s_waitcnt vmcnt(9)
	v_cndmask_b32_e32 v2, 0, v60, vcc
	s_waitcnt vmcnt(8)
	v_cndmask_b32_e32 v38, 0, v61, vcc
	ds_write2_b32 v31, v2, v38 offset0:172 offset1:238
	s_waitcnt vmcnt(7)
	v_cndmask_b32_e32 v2, 0, v62, vcc
	s_waitcnt vmcnt(6)
	v_cndmask_b32_e32 v38, 0, v46, vcc
	ds_write2_b32 v32, v2, v38 offset0:48 offset1:114
	s_waitcnt vmcnt(5)
	v_cndmask_b32_e32 v2, 0, v47, vcc
	s_waitcnt vmcnt(4)
	v_cndmask_b32_e32 v38, 0, v48, vcc
	ds_write2_b32 v32, v2, v38 offset0:180 offset1:246
	s_waitcnt vmcnt(3)
	v_cndmask_b32_e32 v2, 0, v49, vcc
	s_waitcnt vmcnt(2)
	v_cndmask_b32_e32 v38, 0, v54, vcc
	ds_write2_b32 v33, v2, v38 offset0:56 offset1:122
	v_lshl_add_u64 v[62:63], v[40:41], 1, v[14:15]
	v_lshl_add_u64 v[68:69], v[62:63], 0, v[68:69]
	s_waitcnt vmcnt(1)
	v_cndmask_b32_e32 v2, 0, v39, vcc
	s_waitcnt vmcnt(0)
	v_cndmask_b32_e32 v38, 0, v42, vcc
	ds_write2_b32 v33, v2, v38 offset0:188 offset1:254
	s_waitcnt lgkmcnt(0)
	ds_read2_b32 v[42:43], v19 offset0:33 offset1:41
	ds_read2_b32 v[44:45], v19 offset1:8
	ds_read2_b32 v[46:47], v19 offset0:66 offset1:74
	ds_read2_b32 v[48:49], v19 offset0:99 offset1:107
	ds_read2_b32 v[54:55], v19 offset0:132 offset1:140
	ds_read2_b32 v[56:57], v19 offset0:165 offset1:173
	ds_read2_b32 v[58:59], v19 offset0:198 offset1:206
	ds_read2_b32 v[60:61], v19 offset0:231 offset1:239
	s_waitcnt lgkmcnt(6)
	v_cvt_pk_bf16_f32 v38, v44, v42
	s_waitcnt lgkmcnt(4)
	v_cvt_pk_bf16_f32 v39, v46, v48
	s_waitcnt lgkmcnt(2)
	v_cvt_pk_bf16_f32 v40, v54, v56
	v_add_u32_e32 v42, 8, v66
	s_waitcnt lgkmcnt(0)
	v_cvt_pk_bf16_f32 v41, v58, v60
	global_store_dwordx4 v[68:69], v[38:41], off
	s_nop 1
	v_cvt_pk_bf16_f32 v38, v45, v43
	v_ashrrev_i32_e32 v43, 31, v42
	v_cvt_pk_bf16_f32 v39, v47, v49
	v_cvt_pk_bf16_f32 v40, v55, v57
	v_cvt_pk_bf16_f32 v41, v59, v61
	v_lshlrev_b64 v[42:43], 11, v[42:43]
	ds_read2_b32 v[44:45], v19 offset0:49 offset1:57
	ds_read2_b32 v[46:47], v19 offset0:16 offset1:24
	ds_read2_b32 v[48:49], v19 offset0:82 offset1:90
	ds_read2_b32 v[54:55], v19 offset0:115 offset1:123
	ds_read2_b32 v[56:57], v19 offset0:148 offset1:156
	ds_read2_b32 v[58:59], v19 offset0:181 offset1:189
	ds_read2_b32 v[60:61], v19 offset0:214 offset1:222
	ds_read2_b32 v[68:69], v19 offset0:247 offset1:255
	v_lshl_add_u64 v[42:43], v[62:63], 0, v[42:43]
	global_store_dwordx4 v[42:43], v[38:41], off
	v_add_u32_e32 v42, 16, v66
	v_ashrrev_i32_e32 v43, 31, v42
	v_lshlrev_b64 v[42:43], 11, v[42:43]
	s_waitcnt lgkmcnt(6)
	v_cvt_pk_bf16_f32 v38, v46, v44
	s_waitcnt lgkmcnt(4)
	v_cvt_pk_bf16_f32 v39, v48, v54
	s_waitcnt lgkmcnt(2)
	v_cvt_pk_bf16_f32 v40, v56, v58
	s_waitcnt lgkmcnt(0)
	v_cvt_pk_bf16_f32 v41, v60, v68
	v_lshl_add_u64 v[42:43], v[62:63], 0, v[42:43]
	global_store_dwordx4 v[42:43], v[38:41], off
	v_add_u32_e32 v42, 24, v66
	v_ashrrev_i32_e32 v43, 31, v42
	v_lshlrev_b64 v[42:43], 11, v[42:43]
	v_cvt_pk_bf16_f32 v38, v47, v45
	v_cvt_pk_bf16_f32 v39, v49, v55
	v_cvt_pk_bf16_f32 v40, v57, v59
	v_cvt_pk_bf16_f32 v41, v61, v69
	v_lshl_add_u64 v[42:43], v[62:63], 0, v[42:43]
	global_store_dwordx4 v[42:43], v[38:41], off
	s_waitcnt lgkmcnt(0)

.LBB0_11:
	s_movk_i32 s14, 0x47f
	v_cmp_lt_i32_e32 vcc, s14, v36
	s_and_saveexec_b64 s[14:15], vcc
	s_xor_b64 s[14:15], exec, s[14:15]
	s_cbranch_execz .LBB0_33
	s_movk_i32 s36, 0x50f
	v_cmp_lt_u32_e32 vcc, s36, v36
	s_and_saveexec_b64 s[36:37], vcc
	s_xor_b64 s[74:75], exec, s[36:37]
	s_cbranch_execz .LBB0_30
	s_movk_i32 s36, 0x54f
	v_cmp_lt_u32_e32 vcc, s36, v36
	s_and_saveexec_b64 s[36:37], vcc
	s_xor_b64 s[76:77], exec, s[36:37]
	s_cbranch_execz .LBB0_27
	s_movk_i32 s36, 0x58f
	v_cmp_lt_u32_e32 vcc, s36, v36
	s_and_saveexec_b64 s[36:37], vcc
	s_xor_b64 s[78:79], exec, s[36:37]
	s_cbranch_execz .LBB0_24
	s_movk_i32 s36, 0x78f
	v_cmp_lt_u32_e32 vcc, s36, v36
	s_and_saveexec_b64 s[36:37], vcc
	s_xor_b64 s[80:81], exec, s[36:37]
	s_cbranch_execz .LBB0_21
	s_movk_i32 s36, 0x128f
	v_cmp_lt_u32_e32 vcc, s36, v36
	s_and_saveexec_b64 s[36:37], vcc
	s_xor_b64 s[82:83], exec, s[36:37]
	s_cbranch_execz .LBB0_18
	v_add_u16_e32 v2, 0xed70, v36
	v_lshrrev_b16_e32 v37, 5, v2
	v_lshlrev_b16_e32 v2, 5, v2
	v_and_b32_e32 v2, 0x3e0, v2
	s_load_dwordx16 s[36:51], s[62:63], 0x80
	v_and_b32_e32 v53, 0xffff, v2
	v_lshlrev_b32_e32 v2, 16, v37
	v_lshl_or_b32 v2, v16, 10, v2
	v_or3_b32 v2, v2, v53, v25
	v_lshlrev_b32_e32 v2, 2, v2
	s_waitcnt lgkmcnt(0)
	v_lshl_add_u64 v[38:39], s[46:47], 0, v[2:3]
	v_add_co_u32_e32 v40, vcc, 0x2000, v38
	global_load_dword v2, v2, s[46:47]
	s_nop 0
	v_addc_co_u32_e32 v41, vcc, 0, v39, vcc
	v_add_co_u32_e32 v42, vcc, 0x4000, v38
	s_nop 1
	v_addc_co_u32_e32 v43, vcc, 0, v39, vcc
	v_add_co_u32_e32 v44, vcc, 0x6000, v38
	s_nop 1
	v_addc_co_u32_e32 v45, vcc, 0, v39, vcc
	v_add_co_u32_e32 v46, vcc, 0x8000, v38
	s_nop 1
	v_addc_co_u32_e32 v47, vcc, 0, v39, vcc
	v_add_co_u32_e32 v48, vcc, 0xa000, v38
	s_nop 1
	v_addc_co_u32_e32 v49, vcc, 0, v39, vcc
	v_add_co_u32_e32 v54, vcc, 0xc000, v38
	s_nop 1
	v_addc_co_u32_e32 v55, vcc, 0, v39, vcc
	v_add_co_u32_e32 v56, vcc, 0xe000, v38
	s_nop 1
	v_addc_co_u32_e32 v57, vcc, 0, v39, vcc
	v_add_co_u32_e32 v58, vcc, 0x10000, v38
	s_nop 1
	v_addc_co_u32_e32 v59, vcc, 0, v39, vcc
	global_load_dword v60, v[40:41], off nt
	global_load_dword v61, v[42:43], off nt
	global_load_dword v62, v[44:45], off nt
	global_load_dword v63, v[46:47], off nt
	global_load_dword v64, v[48:49], off nt
	global_load_dword v66, v[54:55], off nt
	global_load_dword v67, v[56:57], off nt
	global_load_dword v68, v[58:59], off nt
	v_add_co_u32_e32 v40, vcc, 0x12000, v38
	s_nop 1
	v_addc_co_u32_e32 v41, vcc, 0, v39, vcc
	v_add_co_u32_e32 v42, vcc, 0x14000, v38
	s_nop 1
	v_addc_co_u32_e32 v43, vcc, 0, v39, vcc
	v_add_co_u32_e32 v44, vcc, 0x16000, v38
	s_nop 1
	v_addc_co_u32_e32 v45, vcc, 0, v39, vcc
	v_add_co_u32_e32 v46, vcc, 0x18000, v38
	s_nop 1
	v_addc_co_u32_e32 v47, vcc, 0, v39, vcc
	v_add_co_u32_e32 v48, vcc, 0x1a000, v38
	s_nop 1
	v_addc_co_u32_e32 v49, vcc, 0, v39, vcc
	v_add_co_u32_e32 v54, vcc, 0x1c000, v38
	s_nop 1
	v_addc_co_u32_e32 v55, vcc, 0, v39, vcc
	v_add_co_u32_e32 v56, vcc, 0x1e000, v38
	s_nop 1
	v_addc_co_u32_e32 v57, vcc, 0, v39, vcc
	v_add_co_u32_e32 v58, vcc, 0x20000, v38
	s_nop 1
	v_addc_co_u32_e32 v59, vcc, 0, v39, vcc
	global_load_dword v69, v[40:41], off nt
	global_load_dword v70, v[42:43], off nt
	global_load_dword v71, v[44:45], off nt
	global_load_dword v72, v[46:47], off nt
	global_load_dword v73, v[48:49], off nt
	global_load_dword v74, v[54:55], off nt
	global_load_dword v75, v[56:57], off nt
	global_load_dword v76, v[58:59], off nt
	v_add_co_u32_e32 v40, vcc, 0x22000, v38
	s_nop 1
	v_addc_co_u32_e32 v41, vcc, 0, v39, vcc
	v_add_co_u32_e32 v42, vcc, 0x24000, v38
	s_nop 1
	v_addc_co_u32_e32 v43, vcc, 0, v39, vcc
	v_add_co_u32_e32 v44, vcc, 0x26000, v38
	s_nop 1
	v_addc_co_u32_e32 v45, vcc, 0, v39, vcc
	v_add_co_u32_e32 v46, vcc, 0x28000, v38
	s_nop 1
	v_addc_co_u32_e32 v47, vcc, 0, v39, vcc
	v_add_co_u32_e32 v48, vcc, 0x2a000, v38
	s_nop 1
	v_addc_co_u32_e32 v49, vcc, 0, v39, vcc
	v_add_co_u32_e32 v54, vcc, 0x2c000, v38
	s_nop 1
	v_addc_co_u32_e32 v55, vcc, 0, v39, vcc
	v_add_co_u32_e32 v56, vcc, 0x2e000, v38
	s_nop 1
	v_addc_co_u32_e32 v57, vcc, 0, v39, vcc
	v_add_co_u32_e32 v58, vcc, 0x30000, v38
	s_nop 1
	v_addc_co_u32_e32 v59, vcc, 0, v39, vcc
	global_load_dword v77, v[40:41], off nt
	global_load_dword v78, v[42:43], off nt
	global_load_dword v79, v[44:45], off nt
	global_load_dword v80, v[46:47], off nt
	global_load_dword v81, v[48:49], off nt
	global_load_dword v82, v[54:55], off nt
	s_nop 0
	global_load_dword v56, v[56:57], off nt
	s_nop 0
	global_load_dword v57, v[58:59], off nt
	v_add_co_u32_e32 v40, vcc, 0x32000, v38
	s_nop 1
	v_addc_co_u32_e32 v41, vcc, 0, v39, vcc
	v_add_co_u32_e32 v42, vcc, 0x34000, v38
	s_nop 1
	v_addc_co_u32_e32 v43, vcc, 0, v39, vcc
	v_add_co_u32_e32 v44, vcc, 0x36000, v38
	s_nop 1
	v_addc_co_u32_e32 v45, vcc, 0, v39, vcc
	v_add_co_u32_e32 v46, vcc, 0x38000, v38
	s_nop 1
	v_addc_co_u32_e32 v47, vcc, 0, v39, vcc
	v_add_co_u32_e32 v48, vcc, 0x3a000, v38
	s_nop 1
	v_addc_co_u32_e32 v49, vcc, 0, v39, vcc
	v_add_co_u32_e32 v54, vcc, 0x3c000, v38
	s_nop 1
	v_addc_co_u32_e32 v55, vcc, 0, v39, vcc
	v_add_co_u32_e32 v38, vcc, 0x3e000, v38
	s_nop 1
	v_addc_co_u32_e32 v39, vcc, 0, v39, vcc
	global_load_dword v40, v[40:41], off nt
	s_nop 0
	global_load_dword v41, v[42:43], off nt
	s_nop 0
	global_load_dword v42, v[44:45], off nt
	global_load_dword v43, v[46:47], off nt
	s_nop 0
	global_load_dword v44, v[48:49], off nt
	global_load_dword v45, v[54:55], off nt
	s_nop 0
	global_load_dword v38, v[38:39], off nt
	s_waitcnt vmcnt(30)
	ds_write2_b32 v17, v2, v60 offset1:66
	s_waitcnt vmcnt(28)
	ds_write2_b32 v17, v61, v62 offset0:132 offset1:198
	s_waitcnt vmcnt(26)
	ds_write2_b32 v27, v63, v64 offset0:8 offset1:74
	s_waitcnt vmcnt(24)
	ds_write2_b32 v27, v66, v67 offset0:140 offset1:206
	s_waitcnt vmcnt(22)
	ds_write2_b32 v28, v68, v69 offset0:16 offset1:82
	s_waitcnt vmcnt(20)
	ds_write2_b32 v28, v70, v71 offset0:148 offset1:214
	s_waitcnt vmcnt(18)
	ds_write2_b32 v29, v72, v73 offset0:24 offset1:90
	s_waitcnt vmcnt(16)
	ds_write2_b32 v29, v74, v75 offset0:156 offset1:222
	s_waitcnt vmcnt(14)
	ds_write2_b32 v30, v76, v77 offset0:32 offset1:98
	s_waitcnt vmcnt(12)
	ds_write2_b32 v30, v78, v79 offset0:164 offset1:230
	s_waitcnt vmcnt(10)
	ds_write2_b32 v31, v80, v81 offset0:40 offset1:106
	s_waitcnt vmcnt(8)
	ds_write2_b32 v31, v82, v56 offset0:172 offset1:238
	s_waitcnt vmcnt(6)
	ds_write2_b32 v32, v57, v40 offset0:48 offset1:114
	s_waitcnt vmcnt(4)
	ds_write2_b32 v32, v41, v42 offset0:180 offset1:246
	s_waitcnt vmcnt(2)
	ds_write2_b32 v33, v43, v44 offset0:56 offset1:122
	s_waitcnt vmcnt(0)
	ds_write2_b32 v33, v45, v38 offset0:188 offset1:254
	s_waitcnt lgkmcnt(0)
	v_lshlrev_b32_e32 v2, 7, v37
	ds_read2_b32 v[42:43], v19 offset0:33 offset1:41
	ds_read2_b32 v[44:45], v19 offset1:8
	ds_read2_b32 v[46:47], v19 offset0:66 offset1:74
	ds_read2_b32 v[48:49], v19 offset0:99 offset1:107
	ds_read2_b32 v[54:55], v19 offset0:132 offset1:140
	ds_read2_b32 v[56:57], v19 offset0:165 offset1:173
	ds_read2_b32 v[58:59], v19 offset0:198 offset1:206
	ds_read2_b32 v[60:61], v19 offset0:231 offset1:239
	v_lshl_add_u64 v[62:63], v[4:5], 0, v[2:3]
	v_or_b32_e32 v2, v18, v53
	v_mul_u32_u24_e32 v2, 0xb00, v2
	v_lshlrev_b32_e32 v2, 1, v2
	v_lshl_add_u64 v[66:67], v[62:63], 0, v[2:3]
	v_or_b32_e32 v2, v20, v53
	s_waitcnt lgkmcnt(6)
	v_cvt_pk_bf16_f32 v38, v44, v42
	s_waitcnt lgkmcnt(4)
	v_cvt_pk_bf16_f32 v39, v46, v48
	s_waitcnt lgkmcnt(2)
	v_cvt_pk_bf16_f32 v40, v54, v56
	s_waitcnt lgkmcnt(0)
	v_cvt_pk_bf16_f32 v41, v58, v60
	v_mul_u32_u24_e32 v2, 0xb00, v2
	global_store_dwordx4 v[66:67], v[38:41], off
	v_lshlrev_b32_e32 v2, 1, v2
	s_nop 0
	v_cvt_pk_bf16_f32 v38, v45, v43
	v_cvt_pk_bf16_f32 v39, v47, v49
	v_cvt_pk_bf16_f32 v40, v55, v57
	v_cvt_pk_bf16_f32 v41, v59, v61
	v_lshl_add_u64 v[42:43], v[62:63], 0, v[2:3]
	ds_read2_b32 v[44:45], v19 offset0:16 offset1:24
	ds_read2_b32 v[46:47], v19 offset0:49 offset1:57
	ds_read2_b32 v[48:49], v19 offset0:82 offset1:90
	ds_read2_b32 v[54:55], v19 offset0:115 offset1:123
	ds_read2_b32 v[56:57], v19 offset0:148 offset1:156
	ds_read2_b32 v[58:59], v19 offset0:181 offset1:189
	ds_read2_b32 v[60:61], v19 offset0:214 offset1:222
	ds_read2_b32 v[66:67], v19 offset0:247 offset1:255
	v_or_b32_e32 v2, v21, v53
	v_mul_u32_u24_e32 v2, 0xb00, v2
	v_lshlrev_b32_e32 v2, 1, v2
	global_store_dwordx4 v[42:43], v[38:41], off
	v_lshl_add_u64 v[42:43], v[62:63], 0, v[2:3]
	v_or_b32_e32 v2, v22, v53
	v_mul_u32_u24_e32 v2, 0xb00, v2
	s_waitcnt lgkmcnt(6)
	v_cvt_pk_bf16_f32 v38, v44, v46
	s_waitcnt lgkmcnt(4)
	v_cvt_pk_bf16_f32 v39, v48, v54
	s_waitcnt lgkmcnt(2)
	v_cvt_pk_bf16_f32 v40, v56, v58
	s_waitcnt lgkmcnt(0)
	v_cvt_pk_bf16_f32 v41, v60, v66
	v_lshlrev_b32_e32 v2, 1, v2
	global_store_dwordx4 v[42:43], v[38:41], off
	v_lshl_add_u64 v[42:43], v[62:63], 0, v[2:3]
	s_nop 0
	v_cvt_pk_bf16_f32 v38, v45, v47
	v_cvt_pk_bf16_f32 v39, v49, v55
	v_cvt_pk_bf16_f32 v40, v57, v59
	v_cvt_pk_bf16_f32 v41, v61, v67
	global_store_dwordx4 v[42:43], v[38:41], off
	s_waitcnt lgkmcnt(0)
.LBB0_18:
	s_andn2_saveexec_b64 s[82:83], s[82:83]
	s_cbranch_execz .LBB0_20
	v_add_u16_e32 v2, 0xf870, v36
	v_mul_u32_u24_e32 v37, 0xba2f, v2
	v_lshrrev_b32_e32 v37, 23, v37
	v_mul_lo_u16_e32 v38, 0xb0, v37
	v_sub_u16_e32 v2, v2, v38
	s_load_dwordx16 s[36:51], s[62:63], 0x80
	v_lshlrev_b16_e32 v37, 6, v37
	v_lshlrev_b16_e32 v53, 5, v2
	v_lshrrev_b32_e32 v2, 1, v53
	v_or_b32_e32 v38, v16, v37
	v_add_u32_e32 v2, v23, v2
	v_mul_u32_u24_e32 v38, 0x1600, v38
	v_add_lshl_u32 v2, v2, v38, 2
	s_waitcnt lgkmcnt(0)
	v_lshl_add_u64 v[38:39], s[40:41], 0, v[2:3]
	v_add_co_u32_e32 v40, vcc, 0xb000, v38
	s_mov_b32 s36, 0x2c000
	s_nop 0
	v_addc_co_u32_e32 v41, vcc, 0, v39, vcc
	v_add_co_u32_e32 v42, vcc, s4, v38
	global_load_dword v2, v2, s[40:41]
	s_nop 0
	v_addc_co_u32_e32 v43, vcc, 0, v39, vcc
	v_add_co_u32_e32 v44, vcc, 0x21000, v38
	s_nop 1
	v_addc_co_u32_e32 v45, vcc, 0, v39, vcc
	v_add_co_u32_e32 v46, vcc, s36, v38
	s_nop 1
	v_addc_co_u32_e32 v47, vcc, 0, v39, vcc
	v_add_co_u32_e32 v48, vcc, 0x37000, v38
	s_nop 1
	v_addc_co_u32_e32 v49, vcc, 0, v39, vcc
	v_add_co_u32_e32 v54, vcc, 0x42000, v38
	s_nop 1
	v_addc_co_u32_e32 v55, vcc, 0, v39, vcc
	v_add_co_u32_e32 v56, vcc, 0x4d000, v38
	s_nop 1
	v_addc_co_u32_e32 v57, vcc, 0, v39, vcc
	v_add_co_u32_e32 v58, vcc, 0x58000, v38
	s_nop 1
	v_addc_co_u32_e32 v59, vcc, 0, v39, vcc
	global_load_dword v60, v[40:41], off nt
	global_load_dword v61, v[42:43], off nt
	global_load_dword v62, v[44:45], off nt
	global_load_dword v63, v[46:47], off nt
	global_load_dword v64, v[48:49], off nt
	global_load_dword v66, v[54:55], off nt
	global_load_dword v67, v[56:57], off nt
	global_load_dword v68, v[58:59], off nt
	v_add_co_u32_e32 v40, vcc, 0x63000, v38
	s_nop 1
	v_addc_co_u32_e32 v41, vcc, 0, v39, vcc
	v_add_co_u32_e32 v42, vcc, 0x6e000, v38
	s_nop 1
	v_addc_co_u32_e32 v43, vcc, 0, v39, vcc
	v_add_co_u32_e32 v44, vcc, 0x79000, v38
	s_nop 1
	v_addc_co_u32_e32 v45, vcc, 0, v39, vcc
	v_add_co_u32_e32 v46, vcc, 0x84000, v38
	s_nop 1
	v_addc_co_u32_e32 v47, vcc, 0, v39, vcc
	v_add_co_u32_e32 v48, vcc, 0x8f000, v38
	s_nop 1
	v_addc_co_u32_e32 v49, vcc, 0, v39, vcc
	v_add_co_u32_e32 v54, vcc, 0x9a000, v38
	s_nop 1
	v_addc_co_u32_e32 v55, vcc, 0, v39, vcc
	v_add_co_u32_e32 v56, vcc, 0xa5000, v38
	s_nop 1
	v_addc_co_u32_e32 v57, vcc, 0, v39, vcc
	v_add_co_u32_e32 v58, vcc, 0xb0000, v38
	s_nop 1
	v_addc_co_u32_e32 v59, vcc, 0, v39, vcc
	global_load_dword v69, v[40:41], off nt
	global_load_dword v70, v[42:43], off nt
	global_load_dword v71, v[44:45], off nt
	global_load_dword v72, v[46:47], off nt
	global_load_dword v73, v[48:49], off nt
	global_load_dword v74, v[54:55], off nt
	global_load_dword v75, v[56:57], off nt
	global_load_dword v76, v[58:59], off nt
	v_add_co_u32_e32 v40, vcc, 0xbb000, v38
	s_nop 1
	v_addc_co_u32_e32 v41, vcc, 0, v39, vcc
	v_add_co_u32_e32 v42, vcc, 0xc6000, v38
	s_nop 1
	v_addc_co_u32_e32 v43, vcc, 0, v39, vcc
	v_add_co_u32_e32 v44, vcc, 0xd1000, v38
	s_nop 1
	v_addc_co_u32_e32 v45, vcc, 0, v39, vcc
	v_add_co_u32_e32 v46, vcc, 0xdc000, v38
	s_nop 1
	v_addc_co_u32_e32 v47, vcc, 0, v39, vcc
	v_add_co_u32_e32 v48, vcc, 0xe7000, v38
	s_nop 1
	v_addc_co_u32_e32 v49, vcc, 0, v39, vcc
	v_add_co_u32_e32 v54, vcc, 0xf2000, v38
	s_nop 1
	v_addc_co_u32_e32 v55, vcc, 0, v39, vcc
	v_add_co_u32_e32 v56, vcc, 0xfd000, v38
	s_nop 1
	v_addc_co_u32_e32 v57, vcc, 0, v39, vcc
	v_add_co_u32_e32 v58, vcc, 0x108000, v38
	s_nop 1
	v_addc_co_u32_e32 v59, vcc, 0, v39, vcc
	global_load_dword v77, v[40:41], off nt
	global_load_dword v78, v[42:43], off nt
	global_load_dword v79, v[44:45], off nt
	global_load_dword v80, v[46:47], off nt
	global_load_dword v81, v[48:49], off nt
	global_load_dword v82, v[54:55], off nt
	s_nop 0
	global_load_dword v56, v[56:57], off nt
	s_nop 0
	global_load_dword v57, v[58:59], off nt
	v_add_co_u32_e32 v40, vcc, 0x113000, v38
	s_nop 1
	v_addc_co_u32_e32 v41, vcc, 0, v39, vcc
	v_add_co_u32_e32 v42, vcc, 0x11e000, v38
	s_nop 1
	v_addc_co_u32_e32 v43, vcc, 0, v39, vcc
	v_add_co_u32_e32 v44, vcc, 0x129000, v38
	s_nop 1
	v_addc_co_u32_e32 v45, vcc, 0, v39, vcc
	v_add_co_u32_e32 v46, vcc, 0x134000, v38
	s_nop 1
	v_addc_co_u32_e32 v47, vcc, 0, v39, vcc
	v_add_co_u32_e32 v48, vcc, 0x13f000, v38
	s_nop 1
	v_addc_co_u32_e32 v49, vcc, 0, v39, vcc
	v_add_co_u32_e32 v54, vcc, 0x14a000, v38
	s_nop 1
	v_addc_co_u32_e32 v55, vcc, 0, v39, vcc
	v_add_co_u32_e32 v38, vcc, 0x155000, v38
	s_nop 1
	v_addc_co_u32_e32 v39, vcc, 0, v39, vcc
	global_load_dword v40, v[40:41], off nt
	s_nop 0
	global_load_dword v41, v[42:43], off nt
	s_nop 0
	global_load_dword v42, v[44:45], off nt
	global_load_dword v43, v[46:47], off nt
	s_nop 0
	global_load_dword v44, v[48:49], off nt
	global_load_dword v45, v[54:55], off nt
	s_nop 0
	global_load_dword v38, v[38:39], off nt
	s_waitcnt vmcnt(30)
	ds_write2_b32 v17, v2, v60 offset1:66
	s_waitcnt vmcnt(28)
	ds_write2_b32 v17, v61, v62 offset0:132 offset1:198
	s_waitcnt vmcnt(26)
	ds_write2_b32 v27, v63, v64 offset0:8 offset1:74
	s_waitcnt vmcnt(24)
	ds_write2_b32 v27, v66, v67 offset0:140 offset1:206
	s_waitcnt vmcnt(22)
	ds_write2_b32 v28, v68, v69 offset0:16 offset1:82
	s_waitcnt vmcnt(20)
	ds_write2_b32 v28, v70, v71 offset0:148 offset1:214
	s_waitcnt vmcnt(18)
	ds_write2_b32 v29, v72, v73 offset0:24 offset1:90
	s_waitcnt vmcnt(16)
	ds_write2_b32 v29, v74, v75 offset0:156 offset1:222
	s_waitcnt vmcnt(14)
	ds_write2_b32 v30, v76, v77 offset0:32 offset1:98
	s_waitcnt vmcnt(12)
	ds_write2_b32 v30, v78, v79 offset0:164 offset1:230
	s_waitcnt vmcnt(10)
	ds_write2_b32 v31, v80, v81 offset0:40 offset1:106
	s_waitcnt vmcnt(8)
	ds_write2_b32 v31, v82, v56 offset0:172 offset1:238
	s_waitcnt vmcnt(6)
	ds_write2_b32 v32, v57, v40 offset0:48 offset1:114
	s_waitcnt vmcnt(4)
	ds_write2_b32 v32, v41, v42 offset0:180 offset1:246
	s_waitcnt vmcnt(2)
	ds_write2_b32 v33, v43, v44 offset0:56 offset1:122
	s_waitcnt vmcnt(0)
	ds_write2_b32 v33, v45, v38 offset0:188 offset1:254
	s_waitcnt lgkmcnt(0)
	ds_read2_b32 v[42:43], v19 offset0:33 offset1:41
	ds_read2_b32 v[44:45], v19 offset1:8
	ds_read2_b32 v[46:47], v19 offset0:66 offset1:74
	ds_read2_b32 v[48:49], v19 offset0:99 offset1:107
	ds_read2_b32 v[54:55], v19 offset0:132 offset1:140
	ds_read2_b32 v[56:57], v19 offset0:165 offset1:173
	ds_read2_b32 v[58:59], v19 offset0:198 offset1:206
	ds_read2_b32 v[60:61], v19 offset0:231 offset1:239
	v_lshlrev_b32_e32 v2, 1, v37
	v_lshl_add_u64 v[62:63], v[6:7], 0, v[2:3]
	v_or_b32_e32 v2, v18, v53
	v_lshlrev_b32_e32 v2, 11, v2
	s_waitcnt lgkmcnt(6)
	v_cvt_pk_bf16_f32 v38, v44, v42
	s_waitcnt lgkmcnt(4)
	v_cvt_pk_bf16_f32 v39, v46, v48
	s_waitcnt lgkmcnt(2)
	v_cvt_pk_bf16_f32 v40, v54, v56
	s_waitcnt lgkmcnt(0)
	v_cvt_pk_bf16_f32 v41, v58, v60
	v_lshl_add_u64 v[66:67], v[62:63], 0, v[2:3]
	global_store_dwordx4 v[66:67], v[38:41], off
	v_or_b32_e32 v2, v20, v53
	v_lshlrev_b32_e32 v2, 11, v2
	v_cvt_pk_bf16_f32 v38, v45, v43
	v_cvt_pk_bf16_f32 v39, v47, v49
	v_cvt_pk_bf16_f32 v40, v55, v57
	v_cvt_pk_bf16_f32 v41, v59, v61
	ds_read2_b32 v[44:45], v19 offset0:49 offset1:57
	ds_read2_b32 v[46:47], v19 offset0:16 offset1:24
	ds_read2_b32 v[48:49], v19 offset0:82 offset1:90
	ds_read2_b32 v[54:55], v19 offset0:115 offset1:123
	ds_read2_b32 v[56:57], v19 offset0:148 offset1:156
	ds_read2_b32 v[58:59], v19 offset0:181 offset1:189
	ds_read2_b32 v[60:61], v19 offset0:214 offset1:222
	ds_read2_b32 v[66:67], v19 offset0:247 offset1:255
	v_lshl_add_u64 v[42:43], v[62:63], 0, v[2:3]
	v_or_b32_e32 v2, v21, v53
	v_lshlrev_b32_e32 v2, 11, v2
	global_store_dwordx4 v[42:43], v[38:41], off
	v_lshl_add_u64 v[42:43], v[62:63], 0, v[2:3]
	v_or_b32_e32 v2, v22, v53
	s_waitcnt lgkmcnt(6)
	v_cvt_pk_bf16_f32 v38, v46, v44
	s_waitcnt lgkmcnt(4)
	v_cvt_pk_bf16_f32 v39, v48, v54
	s_waitcnt lgkmcnt(2)
	v_cvt_pk_bf16_f32 v40, v56, v58
	s_waitcnt lgkmcnt(0)
	v_cvt_pk_bf16_f32 v41, v60, v66
	v_lshlrev_b32_e32 v2, 11, v2
	global_store_dwordx4 v[42:43], v[38:41], off
	v_lshl_add_u64 v[42:43], v[62:63], 0, v[2:3]
	s_nop 0
	v_cvt_pk_bf16_f32 v38, v47, v45
	v_cvt_pk_bf16_f32 v39, v49, v55
	v_cvt_pk_bf16_f32 v40, v57, v59
	v_cvt_pk_bf16_f32 v41, v61, v67
	global_store_dwordx4 v[42:43], v[38:41], off
	s_waitcnt lgkmcnt(0)

.LBB0_21:
	s_andn2_saveexec_b64 s[80:81], s[80:81]
	s_cbranch_execz .LBB0_23
	v_add_u16_e32 v2, 0xfa70, v36
	v_lshrrev_b16_e32 v37, 5, v2
	v_lshlrev_b16_e32 v2, 5, v2
	v_and_b32_e32 v2, 0x3e0, v2
	s_load_dwordx16 s[36:51], s[62:63], 0x80
	v_and_b32_e32 v53, 0xffff, v2
	v_lshlrev_b32_e32 v2, 16, v37
	v_lshl_or_b32 v2, v16, 10, v2
	v_or3_b32 v2, v2, v53, v25
	v_lshlrev_b32_e32 v2, 2, v2
	s_waitcnt lgkmcnt(0)
	v_lshl_add_u64 v[38:39], s[36:37], 0, v[2:3]
	v_add_co_u32_e32 v40, vcc, 0x2000, v38
	global_load_dword v2, v2, s[36:37]
	s_nop 0
	v_addc_co_u32_e32 v41, vcc, 0, v39, vcc
	v_add_co_u32_e32 v42, vcc, 0x4000, v38
	s_nop 1
	v_addc_co_u32_e32 v43, vcc, 0, v39, vcc
	v_add_co_u32_e32 v44, vcc, 0x6000, v38
	s_nop 1
	v_addc_co_u32_e32 v45, vcc, 0, v39, vcc
	v_add_co_u32_e32 v46, vcc, 0x8000, v38
	s_nop 1
	v_addc_co_u32_e32 v47, vcc, 0, v39, vcc
	v_add_co_u32_e32 v48, vcc, 0xa000, v38
	s_nop 1
	v_addc_co_u32_e32 v49, vcc, 0, v39, vcc
	v_add_co_u32_e32 v54, vcc, 0xc000, v38
	s_nop 1
	v_addc_co_u32_e32 v55, vcc, 0, v39, vcc
	v_add_co_u32_e32 v56, vcc, 0xe000, v38
	s_nop 1
	v_addc_co_u32_e32 v57, vcc, 0, v39, vcc
	v_add_co_u32_e32 v58, vcc, 0x10000, v38
	s_nop 1
	v_addc_co_u32_e32 v59, vcc, 0, v39, vcc
	global_load_dword v60, v[40:41], off nt
	global_load_dword v61, v[42:43], off nt
	global_load_dword v62, v[44:45], off nt
	global_load_dword v63, v[46:47], off nt
	global_load_dword v64, v[48:49], off nt
	global_load_dword v66, v[54:55], off nt
	global_load_dword v67, v[56:57], off nt
	global_load_dword v68, v[58:59], off nt
	v_add_co_u32_e32 v40, vcc, 0x12000, v38
	s_nop 1
	v_addc_co_u32_e32 v41, vcc, 0, v39, vcc
	v_add_co_u32_e32 v42, vcc, 0x14000, v38
	s_nop 1
	v_addc_co_u32_e32 v43, vcc, 0, v39, vcc
	v_add_co_u32_e32 v44, vcc, 0x16000, v38
	s_nop 1
	v_addc_co_u32_e32 v45, vcc, 0, v39, vcc
	v_add_co_u32_e32 v46, vcc, 0x18000, v38
	s_nop 1
	v_addc_co_u32_e32 v47, vcc, 0, v39, vcc
	v_add_co_u32_e32 v48, vcc, 0x1a000, v38
	s_nop 1
	v_addc_co_u32_e32 v49, vcc, 0, v39, vcc
	v_add_co_u32_e32 v54, vcc, 0x1c000, v38
	s_nop 1
	v_addc_co_u32_e32 v55, vcc, 0, v39, vcc
	v_add_co_u32_e32 v56, vcc, 0x1e000, v38
	s_nop 1
	v_addc_co_u32_e32 v57, vcc, 0, v39, vcc
	v_add_co_u32_e32 v58, vcc, 0x20000, v38
	s_nop 1
	v_addc_co_u32_e32 v59, vcc, 0, v39, vcc
	global_load_dword v69, v[40:41], off nt
	global_load_dword v70, v[42:43], off nt
	global_load_dword v71, v[44:45], off nt
	global_load_dword v72, v[46:47], off nt
	global_load_dword v73, v[48:49], off nt
	global_load_dword v74, v[54:55], off nt
	global_load_dword v75, v[56:57], off nt
	global_load_dword v76, v[58:59], off nt
	v_add_co_u32_e32 v40, vcc, 0x22000, v38
	s_nop 1
	v_addc_co_u32_e32 v41, vcc, 0, v39, vcc
	v_add_co_u32_e32 v42, vcc, 0x24000, v38
	s_nop 1
	v_addc_co_u32_e32 v43, vcc, 0, v39, vcc
	v_add_co_u32_e32 v44, vcc, 0x26000, v38
	s_nop 1
	v_addc_co_u32_e32 v45, vcc, 0, v39, vcc
	v_add_co_u32_e32 v46, vcc, 0x28000, v38
	s_nop 1
	v_addc_co_u32_e32 v47, vcc, 0, v39, vcc
	v_add_co_u32_e32 v48, vcc, 0x2a000, v38
	s_nop 1
	v_addc_co_u32_e32 v49, vcc, 0, v39, vcc
	v_add_co_u32_e32 v54, vcc, 0x2c000, v38
	s_nop 1
	v_addc_co_u32_e32 v55, vcc, 0, v39, vcc
	v_add_co_u32_e32 v56, vcc, 0x2e000, v38
	s_nop 1
	v_addc_co_u32_e32 v57, vcc, 0, v39, vcc
	v_add_co_u32_e32 v58, vcc, 0x30000, v38
	s_nop 1
	v_addc_co_u32_e32 v59, vcc, 0, v39, vcc
	global_load_dword v77, v[40:41], off nt
	global_load_dword v78, v[42:43], off nt
	global_load_dword v79, v[44:45], off nt
	global_load_dword v80, v[46:47], off nt
	global_load_dword v81, v[48:49], off nt
	global_load_dword v82, v[54:55], off nt
	s_nop 0
	global_load_dword v56, v[56:57], off nt
	s_nop 0
	global_load_dword v57, v[58:59], off nt
	v_add_co_u32_e32 v40, vcc, 0x32000, v38
	s_nop 1
	v_addc_co_u32_e32 v41, vcc, 0, v39, vcc
	v_add_co_u32_e32 v42, vcc, 0x34000, v38
	s_nop 1
	v_addc_co_u32_e32 v43, vcc, 0, v39, vcc
	v_add_co_u32_e32 v44, vcc, 0x36000, v38
	s_nop 1
	v_addc_co_u32_e32 v45, vcc, 0, v39, vcc
	v_add_co_u32_e32 v46, vcc, 0x38000, v38
	s_nop 1
	v_addc_co_u32_e32 v47, vcc, 0, v39, vcc
	v_add_co_u32_e32 v48, vcc, 0x3a000, v38
	s_nop 1
	v_addc_co_u32_e32 v49, vcc, 0, v39, vcc
	v_add_co_u32_e32 v54, vcc, 0x3c000, v38
	s_nop 1
	v_addc_co_u32_e32 v55, vcc, 0, v39, vcc
	v_add_co_u32_e32 v38, vcc, 0x3e000, v38
	s_nop 1
	v_addc_co_u32_e32 v39, vcc, 0, v39, vcc
	global_load_dword v40, v[40:41], off nt
	s_nop 0
	global_load_dword v41, v[42:43], off nt
	s_nop 0
	global_load_dword v42, v[44:45], off nt
	global_load_dword v43, v[46:47], off nt
	s_nop 0
	global_load_dword v44, v[48:49], off nt
	global_load_dword v45, v[54:55], off nt
	s_nop 0
	global_load_dword v38, v[38:39], off nt
	s_waitcnt vmcnt(30)
	ds_write2_b32 v17, v2, v60 offset1:66
	s_waitcnt vmcnt(28)
	ds_write2_b32 v17, v61, v62 offset0:132 offset1:198
	s_waitcnt vmcnt(26)
	ds_write2_b32 v27, v63, v64 offset0:8 offset1:74
	s_waitcnt vmcnt(24)
	ds_write2_b32 v27, v66, v67 offset0:140 offset1:206
	s_waitcnt vmcnt(22)
	ds_write2_b32 v28, v68, v69 offset0:16 offset1:82
	s_waitcnt vmcnt(20)
	ds_write2_b32 v28, v70, v71 offset0:148 offset1:214
	s_waitcnt vmcnt(18)
	ds_write2_b32 v29, v72, v73 offset0:24 offset1:90
	s_waitcnt vmcnt(16)
	ds_write2_b32 v29, v74, v75 offset0:156 offset1:222
	s_waitcnt vmcnt(14)
	ds_write2_b32 v30, v76, v77 offset0:32 offset1:98
	s_waitcnt vmcnt(12)
	ds_write2_b32 v30, v78, v79 offset0:164 offset1:230
	s_waitcnt vmcnt(10)
	ds_write2_b32 v31, v80, v81 offset0:40 offset1:106
	s_waitcnt vmcnt(8)
	ds_write2_b32 v31, v82, v56 offset0:172 offset1:238
	s_waitcnt vmcnt(6)
	ds_write2_b32 v32, v57, v40 offset0:48 offset1:114
	s_waitcnt vmcnt(4)
	ds_write2_b32 v32, v41, v42 offset0:180 offset1:246
	s_waitcnt vmcnt(2)
	ds_write2_b32 v33, v43, v44 offset0:56 offset1:122
	s_waitcnt vmcnt(0)
	ds_write2_b32 v33, v45, v38 offset0:188 offset1:254
	s_waitcnt lgkmcnt(0)
	ds_read2_b32 v[42:43], v19 offset0:33 offset1:41
	ds_read2_b32 v[44:45], v19 offset1:8
	ds_read2_b32 v[46:47], v19 offset0:66 offset1:74
	ds_read2_b32 v[48:49], v19 offset0:99 offset1:107
	ds_read2_b32 v[54:55], v19 offset0:132 offset1:140
	ds_read2_b32 v[56:57], v19 offset0:165 offset1:173
	ds_read2_b32 v[58:59], v19 offset0:198 offset1:206
	ds_read2_b32 v[60:61], v19 offset0:231 offset1:239
	v_lshlrev_b32_e32 v2, 7, v37
	v_lshl_add_u64 v[62:63], v[8:9], 0, v[2:3]
	v_or_b32_e32 v2, v18, v53
	v_lshlrev_b32_e32 v2, 11, v2
	s_waitcnt lgkmcnt(6)
	v_cvt_pk_bf16_f32 v38, v44, v42
	s_waitcnt lgkmcnt(4)
	v_cvt_pk_bf16_f32 v39, v46, v48
	s_waitcnt lgkmcnt(2)
	v_cvt_pk_bf16_f32 v40, v54, v56
	s_waitcnt lgkmcnt(0)
	v_cvt_pk_bf16_f32 v41, v58, v60
	v_lshl_add_u64 v[66:67], v[62:63], 0, v[2:3]
	global_store_dwordx4 v[66:67], v[38:41], off
	v_or_b32_e32 v2, v20, v53
	v_lshlrev_b32_e32 v2, 11, v2
	v_cvt_pk_bf16_f32 v38, v45, v43
	v_cvt_pk_bf16_f32 v39, v47, v49
	v_cvt_pk_bf16_f32 v40, v55, v57
	v_cvt_pk_bf16_f32 v41, v59, v61
	ds_read2_b32 v[44:45], v19 offset0:49 offset1:57
	ds_read2_b32 v[46:47], v19 offset0:16 offset1:24
	ds_read2_b32 v[48:49], v19 offset0:82 offset1:90
	ds_read2_b32 v[54:55], v19 offset0:115 offset1:123
	ds_read2_b32 v[56:57], v19 offset0:148 offset1:156
	ds_read2_b32 v[58:59], v19 offset0:181 offset1:189
	ds_read2_b32 v[60:61], v19 offset0:214 offset1:222
	ds_read2_b32 v[66:67], v19 offset0:247 offset1:255
	v_lshl_add_u64 v[42:43], v[62:63], 0, v[2:3]
	v_or_b32_e32 v2, v21, v53
	v_lshlrev_b32_e32 v2, 11, v2
	global_store_dwordx4 v[42:43], v[38:41], off
	v_lshl_add_u64 v[42:43], v[62:63], 0, v[2:3]
	v_or_b32_e32 v2, v22, v53
	s_waitcnt lgkmcnt(6)
	v_cvt_pk_bf16_f32 v38, v46, v44
	s_waitcnt lgkmcnt(4)
	v_cvt_pk_bf16_f32 v39, v48, v54
	s_waitcnt lgkmcnt(2)
	v_cvt_pk_bf16_f32 v40, v56, v58
	s_waitcnt lgkmcnt(0)
	v_cvt_pk_bf16_f32 v41, v60, v66
	v_lshlrev_b32_e32 v2, 11, v2
	global_store_dwordx4 v[42:43], v[38:41], off
	v_lshl_add_u64 v[42:43], v[62:63], 0, v[2:3]
	s_nop 0
	v_cvt_pk_bf16_f32 v38, v47, v45
	v_cvt_pk_bf16_f32 v39, v49, v55
	v_cvt_pk_bf16_f32 v40, v57, v59
	v_cvt_pk_bf16_f32 v41, v61, v67
	global_store_dwordx4 v[42:43], v[38:41], off
	s_waitcnt lgkmcnt(0)

.LBB0_24:
	s_andn2_saveexec_b64 s[78:79], s[78:79]
	s_cbranch_execz .LBB0_26
	v_and_b32_e32 v37, 0x3c0, v26
	s_load_dwordx16 s[16:31], s[62:63], 0x40
	v_or_b32_e32 v2, v37, v16
	v_and_b32_e32 v53, 0x1e0, v24
	v_lshlrev_b32_e32 v2, 9, v2
	v_or3_b32 v2, v2, v25, v53
	v_lshlrev_b32_e32 v2, 2, v2
	s_waitcnt lgkmcnt(0)
	v_lshl_add_u64 v[38:39], s[30:31], 0, v[2:3]
	v_add_co_u32_e32 v40, vcc, 0x1000, v38
	global_load_dword v2, v2, s[30:31]
	s_nop 0
	v_addc_co_u32_e32 v41, vcc, 0, v39, vcc
	v_add_co_u32_e32 v42, vcc, 0x2000, v38
	v_or_b32_e32 v53, 0x200, v53
	s_nop 0
	v_addc_co_u32_e32 v43, vcc, 0, v39, vcc
	v_add_co_u32_e32 v44, vcc, 0x3000, v38
	s_nop 1
	v_addc_co_u32_e32 v45, vcc, 0, v39, vcc
	v_add_co_u32_e32 v46, vcc, 0x4000, v38
	s_nop 1
	v_addc_co_u32_e32 v47, vcc, 0, v39, vcc
	v_add_co_u32_e32 v48, vcc, 0x5000, v38
	s_nop 1
	v_addc_co_u32_e32 v49, vcc, 0, v39, vcc
	v_add_co_u32_e32 v54, vcc, 0x6000, v38
	s_nop 1
	v_addc_co_u32_e32 v55, vcc, 0, v39, vcc
	v_add_co_u32_e32 v56, vcc, 0x7000, v38
	s_nop 1
	v_addc_co_u32_e32 v57, vcc, 0, v39, vcc
	v_add_co_u32_e32 v58, vcc, 0x8000, v38
	s_nop 1
	v_addc_co_u32_e32 v59, vcc, 0, v39, vcc
	global_load_dword v60, v[40:41], off nt
	global_load_dword v61, v[42:43], off nt
	global_load_dword v62, v[44:45], off nt
	global_load_dword v63, v[46:47], off nt
	global_load_dword v64, v[48:49], off nt
	global_load_dword v66, v[54:55], off nt
	global_load_dword v67, v[56:57], off nt
	global_load_dword v68, v[58:59], off nt
	v_add_co_u32_e32 v40, vcc, 0x9000, v38
	s_nop 1
	v_addc_co_u32_e32 v41, vcc, 0, v39, vcc
	v_add_co_u32_e32 v42, vcc, 0xa000, v38
	s_nop 1
	v_addc_co_u32_e32 v43, vcc, 0, v39, vcc
	v_add_co_u32_e32 v44, vcc, 0xb000, v38
	s_nop 1
	v_addc_co_u32_e32 v45, vcc, 0, v39, vcc
	v_add_co_u32_e32 v46, vcc, 0xc000, v38
	s_nop 1
	v_addc_co_u32_e32 v47, vcc, 0, v39, vcc
	v_add_co_u32_e32 v48, vcc, 0xd000, v38
	s_nop 1
	v_addc_co_u32_e32 v49, vcc, 0, v39, vcc
	v_add_co_u32_e32 v54, vcc, 0xe000, v38
	s_nop 1
	v_addc_co_u32_e32 v55, vcc, 0, v39, vcc
	v_add_co_u32_e32 v56, vcc, 0xf000, v38
	s_nop 1
	v_addc_co_u32_e32 v57, vcc, 0, v39, vcc
	v_add_co_u32_e32 v58, vcc, 0x10000, v38
	s_nop 1
	v_addc_co_u32_e32 v59, vcc, 0, v39, vcc
	global_load_dword v69, v[40:41], off nt
	global_load_dword v70, v[42:43], off nt
	global_load_dword v71, v[44:45], off nt
	global_load_dword v72, v[46:47], off nt
	global_load_dword v73, v[48:49], off nt
	global_load_dword v74, v[54:55], off nt
	global_load_dword v75, v[56:57], off nt
	global_load_dword v76, v[58:59], off nt
	v_add_co_u32_e32 v40, vcc, 0x11000, v38
	s_nop 1
	v_addc_co_u32_e32 v41, vcc, 0, v39, vcc
	v_add_co_u32_e32 v42, vcc, 0x12000, v38
	s_nop 1
	v_addc_co_u32_e32 v43, vcc, 0, v39, vcc
	v_add_co_u32_e32 v44, vcc, 0x13000, v38
	s_nop 1
	v_addc_co_u32_e32 v45, vcc, 0, v39, vcc
	v_add_co_u32_e32 v46, vcc, 0x14000, v38
	s_nop 1
	v_addc_co_u32_e32 v47, vcc, 0, v39, vcc
	v_add_co_u32_e32 v48, vcc, 0x15000, v38
	s_nop 1
	v_addc_co_u32_e32 v49, vcc, 0, v39, vcc
	v_add_co_u32_e32 v54, vcc, 0x16000, v38
	s_nop 1
	v_addc_co_u32_e32 v55, vcc, 0, v39, vcc
	v_add_co_u32_e32 v56, vcc, 0x17000, v38
	s_nop 1
	v_addc_co_u32_e32 v57, vcc, 0, v39, vcc
	v_add_co_u32_e32 v58, vcc, 0x18000, v38
	s_nop 1
	v_addc_co_u32_e32 v59, vcc, 0, v39, vcc
	global_load_dword v77, v[40:41], off nt
	global_load_dword v78, v[42:43], off nt
	global_load_dword v79, v[44:45], off nt
	global_load_dword v80, v[46:47], off nt
	global_load_dword v81, v[48:49], off nt
	global_load_dword v82, v[54:55], off nt
	s_nop 0
	global_load_dword v56, v[56:57], off nt
	s_nop 0
	global_load_dword v57, v[58:59], off nt
	v_add_co_u32_e32 v40, vcc, 0x19000, v38
	s_nop 1
	v_addc_co_u32_e32 v41, vcc, 0, v39, vcc
	v_add_co_u32_e32 v42, vcc, 0x1a000, v38
	s_nop 1
	v_addc_co_u32_e32 v43, vcc, 0, v39, vcc
	v_add_co_u32_e32 v44, vcc, 0x1b000, v38
	s_nop 1
	v_addc_co_u32_e32 v45, vcc, 0, v39, vcc
	v_add_co_u32_e32 v46, vcc, 0x1c000, v38
	s_nop 1
	v_addc_co_u32_e32 v47, vcc, 0, v39, vcc
	v_add_co_u32_e32 v48, vcc, 0x1d000, v38
	s_nop 1
	v_addc_co_u32_e32 v49, vcc, 0, v39, vcc
	v_add_co_u32_e32 v54, vcc, 0x1e000, v38
	s_nop 1
	v_addc_co_u32_e32 v55, vcc, 0, v39, vcc
	v_add_co_u32_e32 v38, vcc, 0x1f000, v38
	s_nop 1
	v_addc_co_u32_e32 v39, vcc, 0, v39, vcc
	global_load_dword v40, v[40:41], off nt
	s_nop 0
	global_load_dword v41, v[42:43], off nt
	s_nop 0
	global_load_dword v42, v[44:45], off nt
	global_load_dword v43, v[46:47], off nt
	s_nop 0
	global_load_dword v44, v[48:49], off nt
	global_load_dword v45, v[54:55], off nt
	s_nop 0
	global_load_dword v38, v[38:39], off nt
	s_waitcnt vmcnt(30)
	ds_write2_b32 v17, v2, v60 offset1:66
	s_waitcnt vmcnt(28)
	ds_write2_b32 v17, v61, v62 offset0:132 offset1:198
	s_waitcnt vmcnt(26)
	ds_write2_b32 v27, v63, v64 offset0:8 offset1:74
	s_waitcnt vmcnt(24)
	ds_write2_b32 v27, v66, v67 offset0:140 offset1:206
	s_waitcnt vmcnt(22)
	ds_write2_b32 v28, v68, v69 offset0:16 offset1:82
	s_waitcnt vmcnt(20)
	ds_write2_b32 v28, v70, v71 offset0:148 offset1:214
	s_waitcnt vmcnt(18)
	ds_write2_b32 v29, v72, v73 offset0:24 offset1:90
	s_waitcnt vmcnt(16)
	ds_write2_b32 v29, v74, v75 offset0:156 offset1:222
	s_waitcnt vmcnt(14)
	ds_write2_b32 v30, v76, v77 offset0:32 offset1:98
	s_waitcnt vmcnt(12)
	ds_write2_b32 v30, v78, v79 offset0:164 offset1:230
	s_waitcnt vmcnt(10)
	ds_write2_b32 v31, v80, v81 offset0:40 offset1:106
	s_waitcnt vmcnt(8)
	ds_write2_b32 v31, v82, v56 offset0:172 offset1:238
	s_waitcnt vmcnt(6)
	ds_write2_b32 v32, v57, v40 offset0:48 offset1:114
	s_waitcnt vmcnt(4)
	ds_write2_b32 v32, v41, v42 offset0:180 offset1:246
	s_waitcnt vmcnt(2)
	ds_write2_b32 v33, v43, v44 offset0:56 offset1:122
	s_waitcnt vmcnt(0)
	ds_write2_b32 v33, v45, v38 offset0:188 offset1:254
	s_waitcnt lgkmcnt(0)
	ds_read2_b32 v[42:43], v19 offset0:33 offset1:41
	ds_read2_b32 v[44:45], v19 offset1:8
	ds_read2_b32 v[46:47], v19 offset0:66 offset1:74
	ds_read2_b32 v[48:49], v19 offset0:99 offset1:107
	ds_read2_b32 v[54:55], v19 offset0:132 offset1:140
	ds_read2_b32 v[56:57], v19 offset0:165 offset1:173
	ds_read2_b32 v[58:59], v19 offset0:198 offset1:206
	ds_read2_b32 v[60:61], v19 offset0:231 offset1:239
	v_lshlrev_b32_e32 v2, 1, v37
	v_lshl_add_u64 v[62:63], v[10:11], 0, v[2:3]
	v_or_b32_e32 v2, v53, v18
	v_lshlrev_b32_e32 v2, 9, v2
	s_waitcnt lgkmcnt(6)
	v_cvt_pk_bf16_f32 v38, v44, v42
	s_waitcnt lgkmcnt(4)
	v_cvt_pk_bf16_f32 v39, v46, v48
	s_waitcnt lgkmcnt(2)
	v_cvt_pk_bf16_f32 v40, v54, v56
	s_waitcnt lgkmcnt(0)
	v_cvt_pk_bf16_f32 v41, v58, v60
	v_lshl_add_u64 v[66:67], v[62:63], 0, v[2:3]
	global_store_dwordx4 v[66:67], v[38:41], off
	v_or_b32_e32 v2, v53, v20
	v_lshlrev_b32_e32 v2, 9, v2
	v_cvt_pk_bf16_f32 v38, v45, v43
	v_cvt_pk_bf16_f32 v39, v47, v49
	v_cvt_pk_bf16_f32 v40, v55, v57
	v_cvt_pk_bf16_f32 v41, v59, v61
	ds_read2_b32 v[44:45], v19 offset0:49 offset1:57
	ds_read2_b32 v[46:47], v19 offset0:16 offset1:24
	ds_read2_b32 v[48:49], v19 offset0:82 offset1:90
	ds_read2_b32 v[54:55], v19 offset0:115 offset1:123
	ds_read2_b32 v[56:57], v19 offset0:148 offset1:156
	ds_read2_b32 v[58:59], v19 offset0:181 offset1:189
	ds_read2_b32 v[60:61], v19 offset0:214 offset1:222
	ds_read2_b32 v[66:67], v19 offset0:247 offset1:255
	v_lshl_add_u64 v[42:43], v[62:63], 0, v[2:3]
	v_or_b32_e32 v2, v53, v21
	v_lshlrev_b32_e32 v2, 9, v2
	global_store_dwordx4 v[42:43], v[38:41], off
	v_lshl_add_u64 v[42:43], v[62:63], 0, v[2:3]
	v_or_b32_e32 v2, v53, v22
	s_waitcnt lgkmcnt(6)
	v_cvt_pk_bf16_f32 v38, v46, v44
	s_waitcnt lgkmcnt(4)
	v_cvt_pk_bf16_f32 v39, v48, v54
	s_waitcnt lgkmcnt(2)
	v_cvt_pk_bf16_f32 v40, v56, v58
	s_waitcnt lgkmcnt(0)
	v_cvt_pk_bf16_f32 v41, v60, v66
	v_lshlrev_b32_e32 v2, 9, v2
	global_store_dwordx4 v[42:43], v[38:41], off
	v_lshl_add_u64 v[42:43], v[62:63], 0, v[2:3]
	s_nop 0
	v_cvt_pk_bf16_f32 v38, v47, v45
	v_cvt_pk_bf16_f32 v39, v49, v55
	v_cvt_pk_bf16_f32 v40, v57, v59
	v_cvt_pk_bf16_f32 v41, v61, v67
	global_store_dwordx4 v[42:43], v[38:41], off
	s_waitcnt lgkmcnt(0)

.LBB0_27:
	s_andn2_saveexec_b64 s[76:77], s[76:77]
	s_cbranch_execz .LBB0_29
	v_add_u32_e32 v2, 0x100, v26
	v_and_b32_e32 v37, 0x3c0, v2
	s_load_dwordx16 s[16:31], s[62:63], 0x40
	v_or_b32_e32 v2, v37, v16
	v_and_b32_e32 v53, 0x1e0, v24
	v_lshlrev_b32_e32 v2, 9, v2
	v_or3_b32 v2, v2, v25, v53
	v_lshlrev_b32_e32 v2, 2, v2
	s_waitcnt lgkmcnt(0)
	v_lshl_add_u64 v[38:39], s[28:29], 0, v[2:3]
	v_add_co_u32_e32 v40, vcc, 0x1000, v38
	s_movk_i32 s36, 0x2000
	s_nop 0
	v_addc_co_u32_e32 v41, vcc, 0, v39, vcc
	v_add_co_u32_e32 v42, vcc, s36, v38
	s_mov_b32 s36, 0x8000
	s_nop 0
	v_addc_co_u32_e32 v43, vcc, 0, v39, vcc
	v_add_co_u32_e32 v44, vcc, 0x3000, v38
	s_nop 1
	v_addc_co_u32_e32 v45, vcc, 0, v39, vcc
	v_add_co_u32_e32 v46, vcc, s2, v38
	s_nop 1
	v_addc_co_u32_e32 v47, vcc, 0, v39, vcc
	v_add_co_u32_e32 v48, vcc, 0x5000, v38
	s_nop 1
	v_addc_co_u32_e32 v49, vcc, 0, v39, vcc
	v_add_co_u32_e32 v54, vcc, s3, v38
	s_nop 1
	v_addc_co_u32_e32 v55, vcc, 0, v39, vcc
	v_add_co_u32_e32 v56, vcc, 0x7000, v38
	s_nop 1
	v_addc_co_u32_e32 v57, vcc, 0, v39, vcc
	v_add_co_u32_e32 v58, vcc, s36, v38
	s_mov_b32 s36, 0xb000
	s_nop 0
	v_addc_co_u32_e32 v59, vcc, 0, v39, vcc
	global_load_dword v60, v[40:41], off nt
	global_load_dword v61, v[42:43], off nt
	global_load_dword v62, v[44:45], off nt
	global_load_dword v63, v[46:47], off nt
	s_nop 0
	global_load_dword v48, v[48:49], off nt
	s_nop 0
	global_load_dword v49, v[54:55], off nt
	s_nop 0
	global_load_dword v54, v[56:57], off nt
	global_load_dword v55, v[58:59], off nt
	v_add_co_u32_e32 v40, vcc, 0x9000, v38
	s_nop 1
	v_addc_co_u32_e32 v41, vcc, 0, v39, vcc
	v_add_co_u32_e32 v42, vcc, s36, v38
	s_mov_b32 s36, 0x11000
	s_nop 0
	v_addc_co_u32_e32 v43, vcc, 0, v39, vcc
	v_add_co_u32_e32 v44, vcc, s5, v38
	s_nop 1
	v_addc_co_u32_e32 v45, vcc, 0, v39, vcc
	v_add_co_u32_e32 v46, vcc, s9, v38
	s_nop 1
	v_addc_co_u32_e32 v47, vcc, 0, v39, vcc
	global_load_dword v2, v2, s[28:29]
	s_nop 0
	global_load_dword v56, v[42:43], off offset:-4096 nt
	global_load_dword v57, v[42:43], off nt
	global_load_dword v58, v[44:45], off offset:-4096 nt
	global_load_dword v59, v[44:45], off nt
	global_load_dword v64, v[46:47], off offset:-4096 nt
	global_load_dword v66, v[46:47], off nt
	global_load_dword v67, v[40:41], off nt
	v_add_co_u32_e32 v40, vcc, s36, v38
	s_mov_b32 s36, 0x17000
	s_nop 0
	v_addc_co_u32_e32 v41, vcc, 0, v39, vcc
	v_add_co_u32_e32 v42, vcc, s33, v38
	s_nop 1
	v_addc_co_u32_e32 v43, vcc, 0, v39, vcc
	v_add_co_u32_e32 v44, vcc, s52, v38
	s_nop 1
	v_addc_co_u32_e32 v45, vcc, 0, v39, vcc
	v_add_co_u32_e32 v46, vcc, s36, v38
	s_mov_b32 s36, 0x1d000
	s_nop 0
	v_addc_co_u32_e32 v47, vcc, 0, v39, vcc
	global_load_dword v68, v[40:41], off offset:-4096 nt
	global_load_dword v69, v[40:41], off nt
	global_load_dword v70, v[42:43], off offset:-4096 nt
	global_load_dword v71, v[42:43], off nt
	global_load_dword v72, v[44:45], off offset:-4096 nt
	global_load_dword v73, v[44:45], off nt
	global_load_dword v74, v[46:47], off offset:-4096 nt
	s_nop 0
	global_load_dword v46, v[46:47], off nt
	v_add_co_u32_e32 v40, vcc, s53, v38
	s_nop 1
	v_addc_co_u32_e32 v41, vcc, 0, v39, vcc
	v_add_co_u32_e32 v42, vcc, s54, v38
	s_nop 1
	v_addc_co_u32_e32 v43, vcc, 0, v39, vcc
	v_add_co_u32_e32 v44, vcc, s36, v38
	s_nop 1
	v_addc_co_u32_e32 v45, vcc, 0, v39, vcc
	v_add_co_u32_e32 v38, vcc, s55, v38
	s_nop 1
	v_addc_co_u32_e32 v39, vcc, 0, v39, vcc
	global_load_dword v47, v[40:41], off offset:-4096 nt
	s_nop 0
	global_load_dword v40, v[40:41], off nt
	s_nop 0
	global_load_dword v41, v[42:43], off offset:-4096 nt
	s_nop 0
	global_load_dword v42, v[42:43], off nt
	s_nop 0
	global_load_dword v43, v[44:45], off offset:-4096 nt
	s_nop 0
	global_load_dword v44, v[44:45], off nt
	s_nop 0
	global_load_dword v45, v[38:39], off offset:-4096 nt
	s_nop 0
	global_load_dword v38, v[38:39], off nt
	s_waitcnt vmcnt(23)
	ds_write2_b32 v17, v2, v60 offset1:66
	ds_write2_b32 v17, v61, v62 offset0:132 offset1:198
	ds_write2_b32 v27, v63, v48 offset0:8 offset1:74
	ds_write2_b32 v27, v49, v54 offset0:140 offset1:206
	s_waitcnt vmcnt(16)
	ds_write2_b32 v28, v55, v67 offset0:16 offset1:82
	ds_write2_b32 v28, v56, v57 offset0:148 offset1:214
	ds_write2_b32 v29, v58, v59 offset0:24 offset1:90
	ds_write2_b32 v29, v64, v66 offset0:156 offset1:222
	s_waitcnt vmcnt(14)
	ds_write2_b32 v30, v68, v69 offset0:32 offset1:98
	s_waitcnt vmcnt(12)
	ds_write2_b32 v30, v70, v71 offset0:164 offset1:230
	s_waitcnt vmcnt(10)
	ds_write2_b32 v31, v72, v73 offset0:40 offset1:106
	s_waitcnt vmcnt(8)
	ds_write2_b32 v31, v74, v46 offset0:172 offset1:238
	s_waitcnt vmcnt(6)
	ds_write2_b32 v32, v47, v40 offset0:48 offset1:114
	s_waitcnt vmcnt(4)
	ds_write2_b32 v32, v41, v42 offset0:180 offset1:246
	s_waitcnt vmcnt(2)
	ds_write2_b32 v33, v43, v44 offset0:56 offset1:122
	s_waitcnt vmcnt(0)
	ds_write2_b32 v33, v45, v38 offset0:188 offset1:254
	s_waitcnt lgkmcnt(0)
	ds_read2_b32 v[42:43], v19 offset0:33 offset1:41
	ds_read2_b32 v[44:45], v19 offset1:8
	ds_read2_b32 v[46:47], v19 offset0:66 offset1:74
	ds_read2_b32 v[48:49], v19 offset0:99 offset1:107
	ds_read2_b32 v[54:55], v19 offset0:132 offset1:140
	ds_read2_b32 v[56:57], v19 offset0:165 offset1:173
	ds_read2_b32 v[58:59], v19 offset0:198 offset1:206
	ds_read2_b32 v[60:61], v19 offset0:231 offset1:239
	v_lshlrev_b32_e32 v2, 1, v37
	v_lshl_add_u64 v[62:63], v[10:11], 0, v[2:3]
	v_or_b32_e32 v2, v53, v18
	v_lshlrev_b32_e32 v2, 9, v2
	s_waitcnt lgkmcnt(6)
	v_cvt_pk_bf16_f32 v38, v44, v42
	s_waitcnt lgkmcnt(4)
	v_cvt_pk_bf16_f32 v39, v46, v48
	s_waitcnt lgkmcnt(2)
	v_cvt_pk_bf16_f32 v40, v54, v56
	s_waitcnt lgkmcnt(0)
	v_cvt_pk_bf16_f32 v41, v58, v60
	v_lshl_add_u64 v[66:67], v[62:63], 0, v[2:3]
	global_store_dwordx4 v[66:67], v[38:41], off
	v_or_b32_e32 v2, v53, v20
	v_lshlrev_b32_e32 v2, 9, v2
	v_cvt_pk_bf16_f32 v38, v45, v43
	v_cvt_pk_bf16_f32 v39, v47, v49
	v_cvt_pk_bf16_f32 v40, v55, v57
	v_cvt_pk_bf16_f32 v41, v59, v61
	ds_read2_b32 v[44:45], v19 offset0:49 offset1:57
	ds_read2_b32 v[46:47], v19 offset0:16 offset1:24
	ds_read2_b32 v[48:49], v19 offset0:82 offset1:90
	ds_read2_b32 v[54:55], v19 offset0:115 offset1:123
	ds_read2_b32 v[56:57], v19 offset0:148 offset1:156
	ds_read2_b32 v[58:59], v19 offset0:181 offset1:189
	ds_read2_b32 v[60:61], v19 offset0:214 offset1:222
	ds_read2_b32 v[66:67], v19 offset0:247 offset1:255
	v_lshl_add_u64 v[42:43], v[62:63], 0, v[2:3]
	v_or_b32_e32 v2, v53, v21
	v_lshlrev_b32_e32 v2, 9, v2
	global_store_dwordx4 v[42:43], v[38:41], off
	v_lshl_add_u64 v[42:43], v[62:63], 0, v[2:3]
	v_or_b32_e32 v2, v53, v22
	s_waitcnt lgkmcnt(6)
	v_cvt_pk_bf16_f32 v38, v46, v44
	s_waitcnt lgkmcnt(4)
	v_cvt_pk_bf16_f32 v39, v48, v54
	s_waitcnt lgkmcnt(2)
	v_cvt_pk_bf16_f32 v40, v56, v58
	s_waitcnt lgkmcnt(0)
	v_cvt_pk_bf16_f32 v41, v60, v66
	v_lshlrev_b32_e32 v2, 9, v2
	global_store_dwordx4 v[42:43], v[38:41], off
	v_lshl_add_u64 v[42:43], v[62:63], 0, v[2:3]
	s_nop 0
	v_cvt_pk_bf16_f32 v38, v47, v45
	v_cvt_pk_bf16_f32 v39, v49, v55
	v_cvt_pk_bf16_f32 v40, v57, v59
	v_cvt_pk_bf16_f32 v41, v61, v67
	global_store_dwordx4 v[42:43], v[38:41], off
	s_waitcnt lgkmcnt(0)

.LBB0_30:
	s_andn2_saveexec_b64 s[74:75], s[74:75]
	s_cbranch_execz .LBB0_32
	s_movk_i32 s36, 0xff
	v_bitop3_b16 v37, v36, s36, v34 bitop3:0x48
	v_mul_lo_u16_e32 v37, 0xab, v37
	v_lshrrev_b16_e32 v37, 12, v37
	v_xor_b32_e32 v2, 0xffffff80, v36
	v_mul_lo_u16_e32 v38, 24, v37
	s_load_dwordx16 s[16:31], s[62:63], 0x40
	v_sub_u16_e32 v2, v2, v38
	v_lshlrev_b32_sdwa v53, v35, v2 dst_sel:DWORD dst_unused:UNUSED_PAD src0_sel:DWORD src1_sel:BYTE_0
	v_lshl_or_b32 v38, v37, 6, v16
	v_or_b32_e32 v2, v53, v25
	v_mul_u32_u24_e32 v38, 0x300, v38
	v_add_lshl_u32 v2, v38, v2, 2
	s_waitcnt lgkmcnt(0)
	v_lshl_add_u64 v[38:39], s[24:25], 0, v[2:3]
	s_movk_i32 s36, 0x1000
	v_add_co_u32_e32 v40, vcc, s36, v38
	s_movk_i32 s36, 0x3000
	s_nop 0
	v_addc_co_u32_e32 v41, vcc, 0, v39, vcc
	v_add_co_u32_e32 v42, vcc, s36, v38
	s_movk_i32 s36, 0x7000
	s_nop 0
	v_addc_co_u32_e32 v43, vcc, 0, v39, vcc
	v_add_co_u32_e32 v44, vcc, s2, v38
	global_load_dword v2, v2, s[24:25]
	s_nop 0
	v_addc_co_u32_e32 v45, vcc, 0, v39, vcc
	v_add_co_u32_e32 v46, vcc, s3, v38
	s_nop 1
	v_addc_co_u32_e32 v47, vcc, 0, v39, vcc
	v_add_co_u32_e32 v48, vcc, s36, v38
	s_mov_b32 s36, 0x9000
	s_nop 0
	v_addc_co_u32_e32 v49, vcc, 0, v39, vcc
	v_add_co_u32_e32 v54, vcc, s36, v38
	s_mov_b32 s36, 0xa000
	s_nop 0
	v_addc_co_u32_e32 v55, vcc, 0, v39, vcc
	v_add_co_u32_e32 v56, vcc, s36, v38
	s_mov_b32 s36, 0xc000
	s_nop 0
	v_addc_co_u32_e32 v57, vcc, 0, v39, vcc
	v_add_co_u32_e32 v58, vcc, s36, v38
	s_mov_b32 s36, 0x10000
	s_nop 0
	v_addc_co_u32_e32 v59, vcc, 0, v39, vcc
	global_load_dword v60, v[40:41], off offset:2048 nt
	global_load_dword v61, v[42:43], off nt
	global_load_dword v62, v[44:45], off offset:2048 nt
	global_load_dword v63, v[46:47], off nt
	global_load_dword v64, v[48:49], off offset:2048 nt
	global_load_dword v66, v[54:55], off nt
	global_load_dword v67, v[56:57], off offset:2048 nt
	global_load_dword v68, v[58:59], off nt
	v_add_co_u32_e32 v40, vcc, s5, v38
	s_nop 1
	v_addc_co_u32_e32 v41, vcc, 0, v39, vcc
	v_add_co_u32_e32 v42, vcc, s9, v38
	s_nop 1
	v_addc_co_u32_e32 v43, vcc, 0, v39, vcc
	v_add_co_u32_e32 v44, vcc, s36, v38
	s_mov_b32 s36, 0x12000
	s_nop 0
	v_addc_co_u32_e32 v45, vcc, 0, v39, vcc
	v_add_co_u32_e32 v46, vcc, s36, v38
	s_mov_b32 s36, 0x18000
	s_nop 0
	v_addc_co_u32_e32 v47, vcc, 0, v39, vcc
	v_add_co_u32_e32 v48, vcc, s33, v38
	s_nop 1
	v_addc_co_u32_e32 v49, vcc, 0, v39, vcc
	v_add_co_u32_e32 v54, vcc, s52, v38
	s_nop 1
	v_addc_co_u32_e32 v55, vcc, 0, v39, vcc
	v_add_co_u32_e32 v56, vcc, s4, v38
	s_nop 1
	v_addc_co_u32_e32 v57, vcc, 0, v39, vcc
	v_add_co_u32_e32 v58, vcc, s36, v38
	s_mov_b32 s36, 0x1c000
	s_nop 0
	v_addc_co_u32_e32 v59, vcc, 0, v39, vcc
	global_load_dword v69, v[40:41], off offset:2048 nt
	global_load_dword v70, v[42:43], off nt
	global_load_dword v71, v[44:45], off offset:2048 nt
	global_load_dword v72, v[46:47], off nt
	global_load_dword v73, v[48:49], off offset:2048 nt
	global_load_dword v74, v[54:55], off nt
	global_load_dword v75, v[56:57], off offset:2048 nt
	global_load_dword v76, v[58:59], off nt
	v_add_co_u32_e32 v40, vcc, s53, v38
	s_nop 1
	v_addc_co_u32_e32 v41, vcc, 0, v39, vcc
	v_add_co_u32_e32 v42, vcc, s54, v38
	s_nop 1
	v_addc_co_u32_e32 v43, vcc, 0, v39, vcc
	v_add_co_u32_e32 v44, vcc, s36, v38
	s_mov_b32 s36, 0x1e000
	s_nop 0
	v_addc_co_u32_e32 v45, vcc, 0, v39, vcc
	v_add_co_u32_e32 v46, vcc, s36, v38
	s_mov_b32 s36, 0x21000
	s_nop 0
	v_addc_co_u32_e32 v47, vcc, 0, v39, vcc
	v_add_co_u32_e32 v48, vcc, s55, v38
	s_nop 1
	v_addc_co_u32_e32 v49, vcc, 0, v39, vcc
	v_add_co_u32_e32 v54, vcc, s36, v38
	s_mov_b32 s36, 0x22000
	s_nop 0
	v_addc_co_u32_e32 v55, vcc, 0, v39, vcc
	v_add_co_u32_e32 v56, vcc, s36, v38
	s_mov_b32 s36, 0x24000
	s_nop 0
	v_addc_co_u32_e32 v57, vcc, 0, v39, vcc
	v_add_co_u32_e32 v58, vcc, s36, v38
	s_mov_b32 s36, 0x25000
	s_nop 0
	v_addc_co_u32_e32 v59, vcc, 0, v39, vcc
	global_load_dword v77, v[40:41], off offset:2048 nt
	global_load_dword v78, v[42:43], off nt
	global_load_dword v79, v[44:45], off offset:2048 nt
	global_load_dword v80, v[46:47], off nt
	global_load_dword v81, v[48:49], off offset:2048 nt
	global_load_dword v82, v[54:55], off nt
	s_nop 0
	global_load_dword v56, v[56:57], off offset:2048 nt
	s_nop 0
	global_load_dword v57, v[58:59], off nt
	v_add_co_u32_e32 v40, vcc, s36, v38
	s_mov_b32 s36, 0x27000
	s_nop 0
	v_addc_co_u32_e32 v41, vcc, 0, v39, vcc
	v_add_co_u32_e32 v42, vcc, s36, v38
	s_mov_b32 s36, 0x28000
	s_nop 0
	v_addc_co_u32_e32 v43, vcc, 0, v39, vcc
	v_add_co_u32_e32 v44, vcc, s36, v38
	s_mov_b32 s36, 0x2a000
	s_nop 0
	v_addc_co_u32_e32 v45, vcc, 0, v39, vcc
	v_add_co_u32_e32 v46, vcc, s36, v38
	s_mov_b32 s36, 0x2b000
	s_nop 0
	v_addc_co_u32_e32 v47, vcc, 0, v39, vcc
	v_add_co_u32_e32 v48, vcc, s36, v38
	s_mov_b32 s36, 0x2d000
	s_nop 0
	v_addc_co_u32_e32 v49, vcc, 0, v39, vcc
	v_add_co_u32_e32 v54, vcc, s36, v38
	s_mov_b32 s36, 0x2e000
	s_nop 0
	v_addc_co_u32_e32 v55, vcc, 0, v39, vcc
	v_add_co_u32_e32 v38, vcc, s36, v38
	s_nop 1
	v_addc_co_u32_e32 v39, vcc, 0, v39, vcc
	global_load_dword v40, v[40:41], off offset:2048 nt
	s_nop 0
	global_load_dword v41, v[42:43], off nt
	s_nop 0
	global_load_dword v42, v[44:45], off offset:2048 nt
	global_load_dword v43, v[46:47], off nt
	s_nop 0
	global_load_dword v44, v[48:49], off offset:2048 nt
	global_load_dword v45, v[54:55], off nt
	s_nop 0
	global_load_dword v38, v[38:39], off offset:2048 nt
	s_waitcnt vmcnt(30)
	ds_write2_b32 v17, v2, v60 offset1:66
	s_waitcnt vmcnt(28)
	ds_write2_b32 v17, v61, v62 offset0:132 offset1:198
	s_waitcnt vmcnt(26)
	ds_write2_b32 v27, v63, v64 offset0:8 offset1:74
	s_waitcnt vmcnt(24)
	ds_write2_b32 v27, v66, v67 offset0:140 offset1:206
	s_waitcnt vmcnt(22)
	ds_write2_b32 v28, v68, v69 offset0:16 offset1:82
	s_waitcnt vmcnt(20)
	ds_write2_b32 v28, v70, v71 offset0:148 offset1:214
	s_waitcnt vmcnt(18)
	ds_write2_b32 v29, v72, v73 offset0:24 offset1:90
	s_waitcnt vmcnt(16)
	ds_write2_b32 v29, v74, v75 offset0:156 offset1:222
	s_waitcnt vmcnt(14)
	ds_write2_b32 v30, v76, v77 offset0:32 offset1:98
	s_waitcnt vmcnt(12)
	ds_write2_b32 v30, v78, v79 offset0:164 offset1:230
	s_waitcnt vmcnt(10)
	ds_write2_b32 v31, v80, v81 offset0:40 offset1:106
	s_waitcnt vmcnt(8)
	ds_write2_b32 v31, v82, v56 offset0:172 offset1:238
	s_waitcnt vmcnt(6)
	ds_write2_b32 v32, v57, v40 offset0:48 offset1:114
	s_waitcnt vmcnt(4)
	ds_write2_b32 v32, v41, v42 offset0:180 offset1:246
	s_waitcnt vmcnt(2)
	ds_write2_b32 v33, v43, v44 offset0:56 offset1:122
	s_waitcnt vmcnt(0)
	ds_write2_b32 v33, v45, v38 offset0:188 offset1:254
	s_waitcnt lgkmcnt(0)
	v_lshlrev_b32_e32 v2, 7, v37
	ds_read2_b32 v[42:43], v19 offset0:33 offset1:41
	ds_read2_b32 v[44:45], v19 offset1:8
	ds_read2_b32 v[46:47], v19 offset0:66 offset1:74
	ds_read2_b32 v[48:49], v19 offset0:99 offset1:107
	ds_read2_b32 v[54:55], v19 offset0:132 offset1:140
	ds_read2_b32 v[56:57], v19 offset0:165 offset1:173
	ds_read2_b32 v[58:59], v19 offset0:198 offset1:206
	ds_read2_b32 v[60:61], v19 offset0:231 offset1:239
	v_lshl_add_u64 v[62:63], v[12:13], 0, v[2:3]
	v_or_b32_e32 v2, v53, v18
	v_mul_u32_u24_e32 v2, 0x180, v2
	v_lshlrev_b32_e32 v2, 1, v2
	v_lshl_add_u64 v[66:67], v[62:63], 0, v[2:3]
	v_or_b32_e32 v2, v53, v20
	s_waitcnt lgkmcnt(6)
	v_cvt_pk_bf16_f32 v38, v44, v42
	s_waitcnt lgkmcnt(4)
	v_cvt_pk_bf16_f32 v39, v46, v48
	s_waitcnt lgkmcnt(2)
	v_cvt_pk_bf16_f32 v40, v54, v56
	s_waitcnt lgkmcnt(0)
	v_cvt_pk_bf16_f32 v41, v58, v60
	v_mul_u32_u24_e32 v2, 0x180, v2
	global_store_dwordx4 v[66:67], v[38:41], off
	v_lshlrev_b32_e32 v2, 1, v2
	s_nop 0
	v_cvt_pk_bf16_f32 v38, v45, v43
	v_cvt_pk_bf16_f32 v39, v47, v49
	v_cvt_pk_bf16_f32 v40, v55, v57
	v_cvt_pk_bf16_f32 v41, v59, v61
	v_lshl_add_u64 v[42:43], v[62:63], 0, v[2:3]
	ds_read2_b32 v[44:45], v19 offset0:16 offset1:24
	ds_read2_b32 v[46:47], v19 offset0:49 offset1:57
	ds_read2_b32 v[48:49], v19 offset0:82 offset1:90
	ds_read2_b32 v[54:55], v19 offset0:115 offset1:123
	ds_read2_b32 v[56:57], v19 offset0:148 offset1:156
	ds_read2_b32 v[58:59], v19 offset0:181 offset1:189
	ds_read2_b32 v[60:61], v19 offset0:214 offset1:222
	ds_read2_b32 v[66:67], v19 offset0:247 offset1:255
	v_or_b32_e32 v2, v53, v21
	v_mul_u32_u24_e32 v2, 0x180, v2
	v_lshlrev_b32_e32 v2, 1, v2
	global_store_dwordx4 v[42:43], v[38:41], off
	v_lshl_add_u64 v[42:43], v[62:63], 0, v[2:3]
	v_or_b32_e32 v2, v53, v22
	v_mul_u32_u24_e32 v2, 0x180, v2
	s_waitcnt lgkmcnt(6)
	v_cvt_pk_bf16_f32 v38, v44, v46
	s_waitcnt lgkmcnt(4)
	v_cvt_pk_bf16_f32 v39, v48, v54
	s_waitcnt lgkmcnt(2)
	v_cvt_pk_bf16_f32 v40, v56, v58
	s_waitcnt lgkmcnt(0)
	v_cvt_pk_bf16_f32 v41, v60, v66
	v_lshlrev_b32_e32 v2, 1, v2
	global_store_dwordx4 v[42:43], v[38:41], off
	v_lshl_add_u64 v[42:43], v[62:63], 0, v[2:3]
	s_nop 0
	v_cvt_pk_bf16_f32 v38, v45, v47
	v_cvt_pk_bf16_f32 v39, v49, v55
	v_cvt_pk_bf16_f32 v40, v57, v59
	v_cvt_pk_bf16_f32 v41, v61, v67
	global_store_dwordx4 v[42:43], v[38:41], off
	s_waitcnt lgkmcnt(0)
